# in-proj (layer 1) GEMM epilogue, non-rotary tiles: 8 row-scale loads issued up front, per-group store/load waits removed, flat stores made global
# baseline (speedup 1.0000x reference)
; __device__ __forceinline__ unsigned cvt_pk_bf16(float lo, float hi) { unsigned r; asm volatile("v_cvt_pk_bf16_f32 %0, %1, %2" : "=v"(r) : "v"(lo), "v"(hi)); return r; }
;     __device__ __forceinline__ void operator()(const f32x4 (&acc)[2][2][4][2], const Unit& u, int wr, int wc, int fr, int fq) const {
;         const int row0 = u.pm * BM + wr * 64 + fr, col0 = u.pn * BM + wc * 32 + 8 * fq;
;         const bool rot = u.pn < 8; const int hh = u.pn & 3; const bool isk = u.pn >= 4;
;         const float l2g = __log2f(1.0f - exp2f(-5.0f - (float)hh));
; #pragma unroll
;         for (int ai = 0; ai < 2; ++ai)
; #pragma unroll
;             for (int m = 0; m < 4; ++m) { const int row = row0 + ai * HALF + m * 16; float s = rs[row];
;                 if (!rot) {
; #pragma unroll
;                     for (int bj = 0; bj < 2; ++bj) { const f32x4 v0 = acc[ai][bj][m][0] * s, v1 = acc[ai][bj][m][1] * s; u32x4 w;
;                         w.x = cvt_pk_bf16(v0[0], v0[1]); w.y = cvt_pk_bf16(v0[2], v0[3]); w.z = cvt_pk_bf16(v1[0], v1[1]); w.w = cvt_pk_bf16(v1[2], v1[3]);
;                         *(u32x4*)(O + (size_t)row * 6144 + col0 + bj * HALF) = w; }
.LBB0_532:
	v_lshl_add_u32 v156, s12, 8, v201
	v_ashrrev_i32_e32 v157, 31, v156
	v_lshl_add_u64 v[158:159], v[156:157], 2, s[16:17]
	flat_load_dword v160, v[158:159]
	global_load_dword v186, v[158:159], off offset:64
	global_load_dword v187, v[158:159], off offset:128
	global_load_dword v188, v[158:159], off offset:192
	global_load_dword v189, v[158:159], off offset:512
	global_load_dword v190, v[158:159], off offset:576
	global_load_dword v191, v[158:159], off offset:640
	global_load_dword v192, v[158:159], off offset:704
	s_cmp_gt_i32 s20, 7
	s_cselect_b64 s[36:37], -1, 0
	s_and_b32 s1, s20, 3
	v_cvt_f32_ubyte0_e32 v130, s1
	s_cmp_lt_i32 s20, 4
	v_sub_f32_e32 v154, 0xc0a00000, v130
	s_mov_b32 s1, 0xc2fc0000
	s_cselect_b64 s[58:59], -1, 0
	s_cmp_gt_i32 s20, 3
	v_cmp_gt_f32_e64 s[12:13], s1, v154
	s_cselect_b64 vcc, -1, 0
	s_and_b64 s[82:83], s[12:13], exec
	v_lshl_or_b32 v16, s20, 8, v204
	s_cselect_b32 s1, 0xffffffc0, 0
	s_cmp_lt_i32 s20, 8
	s_mov_b64 s[20:21], -1
	s_cbranch_scc1 .LBB0_534
	s_waitcnt vmcnt(0) lgkmcnt(0)
	v_pk_mul_f32 v[132:133], v[128:129], v[160:161] op_sel_hi:[1,0]
	v_pk_mul_f32 v[130:131], v[126:127], v[160:161] op_sel_hi:[1,0]
	v_pk_mul_f32 v[134:135], v[124:125], v[160:161] op_sel_hi:[1,0]
	v_pk_mul_f32 v[136:137], v[122:123], v[160:161] op_sel_hi:[1,0]
	v_cvt_pk_bf16_f32 v130, v130, v131
	v_cvt_pk_bf16_f32 v131, v132, v133
	s_nop 0
	v_cvt_pk_bf16_f32 v132, v136, v137
	v_cvt_pk_bf16_f32 v133, v134, v135
	v_mov_b64_e32 v[134:135], s[14:15]
	v_mad_i64_i32 v[134:135], s[20:21], v156, s56, v[134:135]
	v_lshl_add_u64 v[162:163], v[16:17], 1, v[134:135]
	flat_store_dwordx4 v[162:163], v[130:133]
	s_mov_b64 s[20:21], 0
	v_pk_mul_f32 v[134:135], v[116:117], v[160:161] op_sel_hi:[1,0]
	v_pk_mul_f32 v[132:133], v[120:121], v[160:161] op_sel_hi:[1,0]
	v_pk_mul_f32 v[130:131], v[118:119], v[160:161] op_sel_hi:[1,0]
	v_pk_mul_f32 v[136:137], v[114:115], v[160:161] op_sel_hi:[1,0]
	v_cvt_pk_bf16_f32 v130, v130, v131
	v_cvt_pk_bf16_f32 v131, v132, v133
	s_nop 0
	v_cvt_pk_bf16_f32 v132, v136, v137
	v_cvt_pk_bf16_f32 v133, v134, v135

; __device__ __forceinline__ unsigned cvt_pk_bf16(float lo, float hi) { unsigned r; asm volatile("v_cvt_pk_bf16_f32 %0, %1, %2" : "=v"(r) : "v"(lo), "v"(hi)); return r; }
;     __device__ __forceinline__ void operator()(const f32x4 (&acc)[2][2][4][2], const Unit& u, int wr, int wc, int fr, int fq) const {
;     ...
;             for (int m = 0; m < 4; ++m) { const int row = row0 + ai * HALF + m * 16; float s = rs[row];
;                 if (!rot) {
; #pragma unroll
;                     for (int bj = 0; bj < 2; ++bj) { const f32x4 v0 = acc[ai][bj][m][0] * s, v1 = acc[ai][bj][m][1] * s; u32x4 w;
;                         w.x = cvt_pk_bf16(v0[0], v0[1]); w.y = cvt_pk_bf16(v0[2], v0[3]); w.z = cvt_pk_bf16(v1[0], v1[1]); w.w = cvt_pk_bf16(v1[2], v1[3]);
;                         *(u32x4*)(O + (size_t)row * 6144 + col0 + bj * HALF) = w; }
.LBB0_542:
	v_or_b32_e32 v118, 16, v156
	v_ashrrev_i32_e32 v119, 31, v118
	global_store_dwordx4 v[162:163], v[130:133], off offset:256
	v_lshl_add_u64 v[114:115], v[118:119], 2, s[16:17]
	v_mov_b32_e32 v122, v186
	v_cndmask_b32_e64 v114, 0, 1, s[36:37]
	v_cmp_ne_u32_e64 s[12:13], 1, v114
	s_andn2_b64 vcc, exec, s[36:37]
	s_mov_b64 s[20:21], -1
	s_cbranch_vccnz .LBB0_544
	s_nop 0
	v_pk_mul_f32 v[116:117], v[112:113], v[122:123] op_sel_hi:[1,0]
	v_pk_mul_f32 v[114:115], v[110:111], v[122:123] op_sel_hi:[1,0]
	v_pk_mul_f32 v[120:121], v[108:109], v[122:123] op_sel_hi:[1,0]
	v_pk_mul_f32 v[124:125], v[106:107], v[122:123] op_sel_hi:[1,0]
	v_cvt_pk_bf16_f32 v114, v114, v115
	v_cvt_pk_bf16_f32 v115, v116, v117
	v_pk_mul_f32 v[126:127], v[98:99], v[122:123] op_sel_hi:[1,0]
	v_cvt_pk_bf16_f32 v116, v124, v125
	v_cvt_pk_bf16_f32 v117, v120, v121
	v_mov_b64_e32 v[120:121], s[14:15]
	v_mad_i64_i32 v[120:121], s[20:21], v118, s56, v[120:121]
	v_lshl_add_u64 v[120:121], v[16:17], 1, v[120:121]
	global_store_dwordx4 v[120:121], v[114:117], off
	s_mov_b64 s[20:21], 0
	v_pk_mul_f32 v[124:125], v[100:101], v[122:123] op_sel_hi:[1,0]
	v_pk_mul_f32 v[116:117], v[104:105], v[122:123] op_sel_hi:[1,0]
	v_pk_mul_f32 v[114:115], v[102:103], v[122:123] op_sel_hi:[1,0]
	s_nop 0
	v_cvt_pk_bf16_f32 v114, v114, v115
	v_cvt_pk_bf16_f32 v115, v116, v117
	v_cvt_pk_bf16_f32 v116, v126, v127
	v_cvt_pk_bf16_f32 v117, v124, v125

; __device__ __forceinline__ unsigned cvt_pk_bf16(float lo, float hi) { unsigned r; asm volatile("v_cvt_pk_bf16_f32 %0, %1, %2" : "=v"(r) : "v"(lo), "v"(hi)); return r; }
;     __device__ __forceinline__ void operator()(const f32x4 (&acc)[2][2][4][2], const Unit& u, int wr, int wc, int fr, int fq) const {
;     ...
;             for (int m = 0; m < 4; ++m) { const int row = row0 + ai * HALF + m * 16; float s = rs[row];
;                 if (!rot) {
; #pragma unroll
;                     for (int bj = 0; bj < 2; ++bj) { const f32x4 v0 = acc[ai][bj][m][0] * s, v1 = acc[ai][bj][m][1] * s; u32x4 w;
;                         w.x = cvt_pk_bf16(v0[0], v0[1]); w.y = cvt_pk_bf16(v0[2], v0[3]); w.z = cvt_pk_bf16(v1[0], v1[1]); w.w = cvt_pk_bf16(v1[2], v1[3]);
;                         *(u32x4*)(O + (size_t)row * 6144 + col0 + bj * HALF) = w; }
.LBB0_552:
	v_or_b32_e32 v102, 32, v156
	v_ashrrev_i32_e32 v103, 31, v102
	global_store_dwordx4 v[120:121], v[114:117], off offset:256
	v_lshl_add_u64 v[98:99], v[102:103], 2, s[16:17]
	v_mov_b32_e32 v106, v187
	s_and_b64 vcc, exec, s[12:13]
	s_mov_b64 s[20:21], -1
	s_cbranch_vccnz .LBB0_554
	s_nop 0
	v_pk_mul_f32 v[100:101], v[96:97], v[106:107] op_sel_hi:[1,0]
	v_pk_mul_f32 v[98:99], v[94:95], v[106:107] op_sel_hi:[1,0]
	v_pk_mul_f32 v[104:105], v[92:93], v[106:107] op_sel_hi:[1,0]
	v_pk_mul_f32 v[108:109], v[90:91], v[106:107] op_sel_hi:[1,0]
	v_cvt_pk_bf16_f32 v98, v98, v99
	v_cvt_pk_bf16_f32 v99, v100, v101
	v_pk_mul_f32 v[110:111], v[82:83], v[106:107] op_sel_hi:[1,0]
	v_cvt_pk_bf16_f32 v100, v108, v109
	v_cvt_pk_bf16_f32 v101, v104, v105
	v_mov_b64_e32 v[104:105], s[14:15]
	v_mad_i64_i32 v[104:105], s[20:21], v102, s56, v[104:105]
	v_lshl_add_u64 v[104:105], v[16:17], 1, v[104:105]
	global_store_dwordx4 v[104:105], v[98:101], off
	s_mov_b64 s[20:21], 0
	v_pk_mul_f32 v[108:109], v[84:85], v[106:107] op_sel_hi:[1,0]
	v_pk_mul_f32 v[100:101], v[88:89], v[106:107] op_sel_hi:[1,0]
	v_pk_mul_f32 v[98:99], v[86:87], v[106:107] op_sel_hi:[1,0]
	s_nop 0
	v_cvt_pk_bf16_f32 v98, v98, v99
	v_cvt_pk_bf16_f32 v99, v100, v101
	v_cvt_pk_bf16_f32 v100, v110, v111
	v_cvt_pk_bf16_f32 v101, v108, v109

; __device__ __forceinline__ unsigned cvt_pk_bf16(float lo, float hi) { unsigned r; asm volatile("v_cvt_pk_bf16_f32 %0, %1, %2" : "=v"(r) : "v"(lo), "v"(hi)); return r; }
;     __device__ __forceinline__ void operator()(const f32x4 (&acc)[2][2][4][2], const Unit& u, int wr, int wc, int fr, int fq) const {
;     ...
;             for (int m = 0; m < 4; ++m) { const int row = row0 + ai * HALF + m * 16; float s = rs[row];
;                 if (!rot) {
; #pragma unroll
;                     for (int bj = 0; bj < 2; ++bj) { const f32x4 v0 = acc[ai][bj][m][0] * s, v1 = acc[ai][bj][m][1] * s; u32x4 w;
;                         w.x = cvt_pk_bf16(v0[0], v0[1]); w.y = cvt_pk_bf16(v0[2], v0[3]); w.z = cvt_pk_bf16(v1[0], v1[1]); w.w = cvt_pk_bf16(v1[2], v1[3]);
;                         *(u32x4*)(O + (size_t)row * 6144 + col0 + bj * HALF) = w; }
.LBB0_562:
	v_or_b32_e32 v86, 48, v156
	v_ashrrev_i32_e32 v87, 31, v86
	global_store_dwordx4 v[104:105], v[98:101], off offset:256
	v_lshl_add_u64 v[82:83], v[86:87], 2, s[16:17]
	v_mov_b32_e32 v90, v188
	s_and_b64 vcc, exec, s[12:13]
	s_mov_b64 s[20:21], -1
	s_cbranch_vccnz .LBB0_564
	s_nop 0
	v_pk_mul_f32 v[84:85], v[80:81], v[90:91] op_sel_hi:[1,0]
	v_pk_mul_f32 v[82:83], v[78:79], v[90:91] op_sel_hi:[1,0]
	v_pk_mul_f32 v[88:89], v[76:77], v[90:91] op_sel_hi:[1,0]
	v_pk_mul_f32 v[92:93], v[74:75], v[90:91] op_sel_hi:[1,0]
	v_cvt_pk_bf16_f32 v82, v82, v83
	v_cvt_pk_bf16_f32 v83, v84, v85
	v_pk_mul_f32 v[94:95], v[66:67], v[90:91] op_sel_hi:[1,0]
	v_cvt_pk_bf16_f32 v84, v92, v93
	v_cvt_pk_bf16_f32 v85, v88, v89
	v_mov_b64_e32 v[88:89], s[14:15]
	v_mad_i64_i32 v[88:89], s[20:21], v86, s56, v[88:89]
	v_lshl_add_u64 v[88:89], v[16:17], 1, v[88:89]
	global_store_dwordx4 v[88:89], v[82:85], off
	s_mov_b64 s[20:21], 0
	v_pk_mul_f32 v[92:93], v[68:69], v[90:91] op_sel_hi:[1,0]
	v_pk_mul_f32 v[84:85], v[72:73], v[90:91] op_sel_hi:[1,0]
	v_pk_mul_f32 v[82:83], v[70:71], v[90:91] op_sel_hi:[1,0]
	s_nop 0
	v_cvt_pk_bf16_f32 v82, v82, v83
	v_cvt_pk_bf16_f32 v83, v84, v85
	v_cvt_pk_bf16_f32 v84, v94, v95
	v_cvt_pk_bf16_f32 v85, v92, v93

; __device__ __forceinline__ unsigned cvt_pk_bf16(float lo, float hi) { unsigned r; asm volatile("v_cvt_pk_bf16_f32 %0, %1, %2" : "=v"(r) : "v"(lo), "v"(hi)); return r; }
;     __device__ __forceinline__ void operator()(const f32x4 (&acc)[2][2][4][2], const Unit& u, int wr, int wc, int fr, int fq) const {
;     ...
;             for (int m = 0; m < 4; ++m) { const int row = row0 + ai * HALF + m * 16; float s = rs[row];
;                 if (!rot) {
; #pragma unroll
;                     for (int bj = 0; bj < 2; ++bj) { const f32x4 v0 = acc[ai][bj][m][0] * s, v1 = acc[ai][bj][m][1] * s; u32x4 w;
;                         w.x = cvt_pk_bf16(v0[0], v0[1]); w.y = cvt_pk_bf16(v0[2], v0[3]); w.z = cvt_pk_bf16(v1[0], v1[1]); w.w = cvt_pk_bf16(v1[2], v1[3]);
;                         *(u32x4*)(O + (size_t)row * 6144 + col0 + bj * HALF) = w; }
.LBB0_572:
	global_store_dwordx4 v[88:89], v[82:85], off offset:256
	v_mov_b32_e32 v72, v189
	v_add_u32_e32 v73, 0x80, v156
	s_and_b64 vcc, exec, s[12:13]
	s_mov_b64 s[20:21], -1
	s_cbranch_vccnz .LBB0_574
	s_nop 0
	v_pk_mul_f32 v[68:69], v[64:65], v[72:73] op_sel_hi:[1,0]
	v_pk_mul_f32 v[66:67], v[62:63], v[72:73] op_sel_hi:[1,0]
	v_pk_mul_f32 v[70:71], v[60:61], v[72:73] op_sel_hi:[1,0]
	v_pk_mul_f32 v[74:75], v[58:59], v[72:73] op_sel_hi:[1,0]
	v_cvt_pk_bf16_f32 v66, v66, v67
	v_cvt_pk_bf16_f32 v67, v68, v69
	v_pk_mul_f32 v[76:77], v[50:51], v[72:73] op_sel_hi:[1,0]
	v_cvt_pk_bf16_f32 v68, v74, v75
	v_cvt_pk_bf16_f32 v69, v70, v71
	v_mov_b64_e32 v[70:71], s[14:15]
	v_mad_i64_i32 v[70:71], s[20:21], v73, s56, v[70:71]
	v_lshl_add_u64 v[70:71], v[16:17], 1, v[70:71]
	global_store_dwordx4 v[70:71], v[66:69], off
	s_mov_b64 s[20:21], 0
	v_pk_mul_f32 v[74:75], v[52:53], v[72:73] op_sel_hi:[1,0]
	v_pk_mul_f32 v[68:69], v[56:57], v[72:73] op_sel_hi:[1,0]
	v_pk_mul_f32 v[66:67], v[54:55], v[72:73] op_sel_hi:[1,0]
	s_nop 0
	v_cvt_pk_bf16_f32 v66, v66, v67
	v_cvt_pk_bf16_f32 v67, v68, v69
	v_cvt_pk_bf16_f32 v68, v76, v77
	v_cvt_pk_bf16_f32 v69, v74, v75

; __device__ __forceinline__ unsigned cvt_pk_bf16(float lo, float hi) { unsigned r; asm volatile("v_cvt_pk_bf16_f32 %0, %1, %2" : "=v"(r) : "v"(lo), "v"(hi)); return r; }
;     __device__ __forceinline__ void operator()(const f32x4 (&acc)[2][2][4][2], const Unit& u, int wr, int wc, int fr, int fq) const {
;     ...
;             for (int m = 0; m < 4; ++m) { const int row = row0 + ai * HALF + m * 16; float s = rs[row];
;                 if (!rot) {
; #pragma unroll
;                     for (int bj = 0; bj < 2; ++bj) { const f32x4 v0 = acc[ai][bj][m][0] * s, v1 = acc[ai][bj][m][1] * s; u32x4 w;
;                         w.x = cvt_pk_bf16(v0[0], v0[1]); w.y = cvt_pk_bf16(v0[2], v0[3]); w.z = cvt_pk_bf16(v1[0], v1[1]); w.w = cvt_pk_bf16(v1[2], v1[3]);
;                         *(u32x4*)(O + (size_t)row * 6144 + col0 + bj * HALF) = w; }
.LBB0_582:
	global_store_dwordx4 v[70:71], v[66:69], off offset:256
	v_mov_b32_e32 v56, v190
	v_add_u32_e32 v57, 0x90, v156
	s_and_b64 vcc, exec, s[12:13]
	s_mov_b64 s[20:21], -1
	s_cbranch_vccnz .LBB0_584
	s_nop 0
	v_pk_mul_f32 v[52:53], v[48:49], v[56:57] op_sel_hi:[1,0]
	v_pk_mul_f32 v[50:51], v[46:47], v[56:57] op_sel_hi:[1,0]
	v_pk_mul_f32 v[54:55], v[44:45], v[56:57] op_sel_hi:[1,0]
	v_pk_mul_f32 v[58:59], v[42:43], v[56:57] op_sel_hi:[1,0]
	v_cvt_pk_bf16_f32 v50, v50, v51
	v_cvt_pk_bf16_f32 v51, v52, v53
	v_pk_mul_f32 v[60:61], v[34:35], v[56:57] op_sel_hi:[1,0]
	v_cvt_pk_bf16_f32 v52, v58, v59
	v_cvt_pk_bf16_f32 v53, v54, v55
	v_mov_b64_e32 v[54:55], s[14:15]
	v_mad_i64_i32 v[54:55], s[20:21], v57, s56, v[54:55]
	v_lshl_add_u64 v[54:55], v[16:17], 1, v[54:55]
	global_store_dwordx4 v[54:55], v[50:53], off
	s_mov_b64 s[20:21], 0
	v_pk_mul_f32 v[58:59], v[36:37], v[56:57] op_sel_hi:[1,0]
	v_pk_mul_f32 v[52:53], v[40:41], v[56:57] op_sel_hi:[1,0]
	v_pk_mul_f32 v[50:51], v[38:39], v[56:57] op_sel_hi:[1,0]
	s_nop 0
	v_cvt_pk_bf16_f32 v50, v50, v51
	v_cvt_pk_bf16_f32 v51, v52, v53
	v_cvt_pk_bf16_f32 v52, v60, v61
	v_cvt_pk_bf16_f32 v53, v58, v59

; __device__ __forceinline__ unsigned cvt_pk_bf16(float lo, float hi) { unsigned r; asm volatile("v_cvt_pk_bf16_f32 %0, %1, %2" : "=v"(r) : "v"(lo), "v"(hi)); return r; }
;     __device__ __forceinline__ void operator()(const f32x4 (&acc)[2][2][4][2], const Unit& u, int wr, int wc, int fr, int fq) const {
;     ...
;             for (int m = 0; m < 4; ++m) { const int row = row0 + ai * HALF + m * 16; float s = rs[row];
;                 if (!rot) {
; #pragma unroll
;                     for (int bj = 0; bj < 2; ++bj) { const f32x4 v0 = acc[ai][bj][m][0] * s, v1 = acc[ai][bj][m][1] * s; u32x4 w;
;                         w.x = cvt_pk_bf16(v0[0], v0[1]); w.y = cvt_pk_bf16(v0[2], v0[3]); w.z = cvt_pk_bf16(v1[0], v1[1]); w.w = cvt_pk_bf16(v1[2], v1[3]);
;                         *(u32x4*)(O + (size_t)row * 6144 + col0 + bj * HALF) = w; }
.LBB0_592:
	global_store_dwordx4 v[54:55], v[50:53], off offset:256
	v_mov_b32_e32 v40, v191
	v_add_u32_e32 v41, 0xa0, v156
	s_and_b64 vcc, exec, s[12:13]
	s_mov_b64 s[20:21], -1
	s_cbranch_vccnz .LBB0_594
	s_nop 0
	v_pk_mul_f32 v[36:37], v[32:33], v[40:41] op_sel_hi:[1,0]
	v_pk_mul_f32 v[34:35], v[30:31], v[40:41] op_sel_hi:[1,0]
	v_pk_mul_f32 v[38:39], v[28:29], v[40:41] op_sel_hi:[1,0]
	v_pk_mul_f32 v[42:43], v[26:27], v[40:41] op_sel_hi:[1,0]
	v_cvt_pk_bf16_f32 v34, v34, v35
	v_cvt_pk_bf16_f32 v35, v36, v37
	v_pk_mul_f32 v[44:45], v[18:19], v[40:41] op_sel_hi:[1,0]
	v_cvt_pk_bf16_f32 v36, v42, v43
	v_cvt_pk_bf16_f32 v37, v38, v39
	v_mov_b64_e32 v[38:39], s[14:15]
	v_mad_i64_i32 v[38:39], s[20:21], v41, s56, v[38:39]
	v_lshl_add_u64 v[38:39], v[16:17], 1, v[38:39]
	global_store_dwordx4 v[38:39], v[34:37], off
	s_mov_b64 s[20:21], 0
	v_pk_mul_f32 v[42:43], v[20:21], v[40:41] op_sel_hi:[1,0]
	v_pk_mul_f32 v[36:37], v[24:25], v[40:41] op_sel_hi:[1,0]
	v_pk_mul_f32 v[34:35], v[22:23], v[40:41] op_sel_hi:[1,0]
	s_nop 0
	v_cvt_pk_bf16_f32 v34, v34, v35
	v_cvt_pk_bf16_f32 v35, v36, v37
	v_cvt_pk_bf16_f32 v36, v44, v45
	v_cvt_pk_bf16_f32 v37, v42, v43

; __device__ __forceinline__ unsigned cvt_pk_bf16(float lo, float hi) { unsigned r; asm volatile("v_cvt_pk_bf16_f32 %0, %1, %2" : "=v"(r) : "v"(lo), "v"(hi)); return r; }
;     __device__ __forceinline__ void operator()(const f32x4 (&acc)[2][2][4][2], const Unit& u, int wr, int wc, int fr, int fq) const {
;     ...
;             for (int m = 0; m < 4; ++m) { const int row = row0 + ai * HALF + m * 16; float s = rs[row];
;                 if (!rot) {
; #pragma unroll
;                     for (int bj = 0; bj < 2; ++bj) { const f32x4 v0 = acc[ai][bj][m][0] * s, v1 = acc[ai][bj][m][1] * s; u32x4 w;
;                         w.x = cvt_pk_bf16(v0[0], v0[1]); w.y = cvt_pk_bf16(v0[2], v0[3]); w.z = cvt_pk_bf16(v1[0], v1[1]); w.w = cvt_pk_bf16(v1[2], v1[3]);
;                         *(u32x4*)(O + (size_t)row * 6144 + col0 + bj * HALF) = w; }
.LBB0_602:
	global_store_dwordx4 v[38:39], v[34:37], off offset:256
	v_mov_b32_e32 v24, v192
	v_add_u32_e32 v25, 0xb0, v156
	s_and_b64 vcc, exec, s[12:13]
	s_mov_b64 s[12:13], -1
	s_cbranch_vccz .LBB0_605
	s_andn2_b64 vcc, exec, s[12:13]
	s_cbranch_vccz .LBB0_606

; __device__ __forceinline__ unsigned cvt_pk_bf16(float lo, float hi) { unsigned r; asm volatile("v_cvt_pk_bf16_f32 %0, %1, %2" : "=v"(r) : "v"(lo), "v"(hi)); return r; }
;     __device__ __forceinline__ void operator()(const f32x4 (&acc)[2][2][4][2], const Unit& u, int wr, int wc, int fr, int fq) const {
;     ...
;             for (int m = 0; m < 4; ++m) { const int row = row0 + ai * HALF + m * 16; float s = rs[row];
;                 if (!rot) {
; #pragma unroll
;                     for (int bj = 0; bj < 2; ++bj) { const f32x4 v0 = acc[ai][bj][m][0] * s, v1 = acc[ai][bj][m][1] * s; u32x4 w;
;                         w.x = cvt_pk_bf16(v0[0], v0[1]); w.y = cvt_pk_bf16(v0[2], v0[3]); w.z = cvt_pk_bf16(v1[0], v1[1]); w.w = cvt_pk_bf16(v1[2], v1[3]);
;                         *(u32x4*)(O + (size_t)row * 6144 + col0 + bj * HALF) = w; }
.LBB0_605:
	s_nop 0
	v_pk_mul_f32 v[20:21], v[14:15], v[24:25] op_sel_hi:[1,0]
	v_pk_mul_f32 v[18:19], v[12:13], v[24:25] op_sel_hi:[1,0]
	v_pk_mul_f32 v[22:23], v[10:11], v[24:25] op_sel_hi:[1,0]
	v_pk_mul_f32 v[26:27], v[8:9], v[24:25] op_sel_hi:[1,0]
	v_cvt_pk_bf16_f32 v18, v18, v19
	v_cvt_pk_bf16_f32 v19, v20, v21
	v_pk_mul_f32 v[28:29], v[0:1], v[24:25] op_sel_hi:[1,0]
	v_cvt_pk_bf16_f32 v20, v26, v27
	v_cvt_pk_bf16_f32 v21, v22, v23
	v_mov_b64_e32 v[22:23], s[14:15]
	v_mad_i64_i32 v[22:23], s[12:13], v25, s56, v[22:23]
	v_lshl_add_u64 v[22:23], v[16:17], 1, v[22:23]
	global_store_dwordx4 v[22:23], v[18:21], off
	v_pk_mul_f32 v[26:27], v[2:3], v[24:25] op_sel_hi:[1,0]
	s_nop 0
	v_pk_mul_f32 v[20:21], v[6:7], v[24:25] op_sel_hi:[1,0]
	v_pk_mul_f32 v[18:19], v[4:5], v[24:25] op_sel_hi:[1,0]
	s_nop 0
	v_cvt_pk_bf16_f32 v18, v18, v19
	v_cvt_pk_bf16_f32 v19, v20, v21
	v_cvt_pk_bf16_f32 v20, v28, v29
	v_cvt_pk_bf16_f32 v21, v26, v27
	s_cbranch_execnz .LBB0_604
